# t15 + one static s_setprio 1 for the PV waves (waves 4-7, the younger half) over the P5 main loop
# speedup vs baseline: 1.0207x; 1.0038x over previous
; __device__ __forceinline__ int v_rd_base(int lane) { return ((lane & 3) << 3) | (((lane >> 2) & 3) << 6) | (((lane >> 4) & 1) << 5) | (((lane >> 5) & 1) << 8); }
; #define RS_BAR() do { asm volatile("s_waitcnt lgkmcnt(0)" ::: "memory"); __builtin_amdgcn_s_barrier(); asm volatile("" ::: "memory"); } while (0)
; #define VM0() asm volatile("s_waitcnt vmcnt(0)" ::: "memory")
; #define VM0() asm volatile("s_waitcnt vmcnt(0)" ::: "memory")
; template <class Epi>
; __device__ __forceinline__ void attn_rs_body(const bf16* __restrict__ Qb, const bf16* __restrict__ Kc, const bf16* __restrict__ V0c, const bf16* __restrict__ V1c, int NT, char* lds, const Epi& epi) {
;     ...
;   } else {
;     f32x16 o[8] = {};
;     const int vb0 = (int)(uintptr_t)(lds + RS_V) + v_rd_base(lane);
;     const int ow = wid - 4;
;     long vdo[4];
; #pragma unroll
;     for (int i = 0; i < 4; ++i) { const int ci = 64 * (4 * ow + i) + lane, st_ = ci >> 5, w_ = ci & 31, kk = (st_ >> 2) * 8 + (w_ >> 2), c_ = (st_ & 3) * 32 + (w_ & 3) * 8;
;       const int k_ = (kk & ~0xC) | ((kk & 4) << 1) | ((kk & 8) >> 1); vdo[i] = (long)k_ * 128 + c_; }
;     ...
;     RS_BAR();
;     RS_BAR();
;     VDMA(0, 0); VM0();
;     RS_BAR();
;     ...
;     for (int j = 1; j <= NT; ++j) {
.LBB0_499:
	s_setprio 1
	s_ashr_i32 s1, s0, 31
	s_lshl_b64 s[4:5], s[0:1], 21
	s_add_u32 s1, s33, s4
	s_addc_u32 s47, s54, s5
	s_add_u32 s4, s1, 0x8000000
	s_addc_u32 s5, s47, 0
	s_add_u32 s46, s1, 0x8200000
	s_addc_u32 s47, s47, 0
	s_add_i32 s50, s50, -4
	v_and_b32_e32 v2, 32, v181
	v_lshlrev_b32_e32 v3, 3, v181
	s_lshl_b32 s1, s50, 8
	v_and_or_b32 v183, v3, 24, v2
	v_lshrrev_b32_e32 v2, 1, v181
	v_bfe_u32 v8, v181, 2, 2
	v_and_b32_e32 v9, 8, v2
	s_ashr_i32 s71, s1, 4
	v_or3_b32 v2, v9, v8, s71
	v_ashrrev_i32_e32 v3, 31, v2
	v_lshlrev_b64 v[168:169], 7, v[2:3]
	s_lshl_b32 s1, s50, 12
	v_or_b32_e32 v4, v168, v183
	v_mov_b32_e32 v5, v169
	s_add_i32 s51, s1, 0
	v_or_b32_e32 v2, 4, v2
	s_waitcnt lgkmcnt(0)
	s_barrier
	v_lshlrev_b64 v[170:171], 1, v[4:5]
	s_add_i32 s50, s51, 0x8000
	v_ashrrev_i32_e32 v3, 31, v2
	s_waitcnt lgkmcnt(0)
	s_barrier
	v_lshl_add_u64 v[4:5], s[4:5], 0, v[170:171]
	s_mov_b32 m0, s50
	s_add_i32 s1, s51, 0xc000
	v_lshlrev_b64 v[166:167], 7, v[2:3]
	global_load_lds_dwordx4 v[4:5], off
	v_lshl_add_u64 v[6:7], s[46:47], 0, v[170:171]
	s_mov_b32 m0, s1
	s_add_i32 s52, s51, 0x8400
	v_or_b32_e32 v2, v166, v183
	v_mov_b32_e32 v3, v167
	global_load_lds_dwordx4 v[6:7], off
	v_lshl_add_u64 v[4:5], v[4:5], 0, s[10:11]
	s_mov_b32 m0, s52
	s_add_i32 s53, s51, 0xc400
	global_load_lds_dwordx4 v[4:5], off
	v_lshl_add_u64 v[4:5], v[6:7], 0, s[10:11]
	s_mov_b32 m0, s53
	v_lshlrev_b64 v[172:173], 1, v[2:3]
	s_add_i32 s66, s51, 0x8800
	global_load_lds_dwordx4 v[4:5], off
	v_lshl_add_u64 v[2:3], s[4:5], 0, v[172:173]
	s_mov_b32 m0, s66
	s_add_i32 s67, s51, 0xc800
	global_load_lds_dwordx4 v[2:3], off
	v_lshl_add_u64 v[4:5], s[46:47], 0, v[172:173]
	s_mov_b32 m0, s67
	s_add_i32 s68, s51, 0x8c00
	global_load_lds_dwordx4 v[4:5], off
	v_lshl_add_u64 v[2:3], v[2:3], 0, s[10:11]
	s_mov_b32 m0, s68
	s_add_i32 s69, s51, 0xcc00
	global_load_lds_dwordx4 v[2:3], off
	v_lshl_add_u64 v[2:3], v[4:5], 0, s[10:11]
	s_mov_b32 m0, s69
	s_add_i32 s72, 0, 0x8000
	global_load_lds_dwordx4 v[2:3], off
	v_lshlrev_b32_e32 v2, 3, v180
	s_cmp_lg_u32 s72, -1
	v_and_b32_e32 v3, 24, v2
	v_lshlrev_b32_e32 v4, 1, v180
	v_and_b32_e32 v0, 0xc0, v0
	s_cselect_b32 s72, s72, 0
	v_and_b32_e32 v4, 32, v4
	v_and_b32_e32 v2, 0x100, v2
	v_add3_u32 v0, v0, s72, v3
	v_add3_u32 v182, v0, v4, v2
	s_add_i32 s48, s49, s48
	v_or3_b32 v2, v9, s71, v8
	s_add_i32 s48, s48, 64
	v_or_b32_e32 v4, 4, v2
	s_ashr_i32 s49, s48, 31
	v_ashrrev_i32_e32 v5, 31, v4
	v_ashrrev_i32_e32 v3, 31, v2
	s_lshl_b64 s[48:49], s[48:49], 21
	v_lshlrev_b64 v[4:5], 8, v[4:5]
	v_lshlrev_b64 v[2:3], 8, v[2:3]
	v_lshl_add_u64 v[4:5], s[48:49], 0, v[4:5]
	v_lshlrev_b32_e32 v0, 1, v183
	v_lshl_add_u64 v[2:3], s[48:49], 0, v[2:3]
	s_waitcnt vmcnt(0)
	v_or_b32_e32 v4, v4, v0
	v_or_b32_e32 v2, v2, v0
	v_mov_b32_e32 v14, v1
	v_mov_b32_e32 v15, v1
	s_waitcnt lgkmcnt(0)
	s_barrier
	v_lshl_add_u64 v[174:175], s[90:91], 0, v[4:5]
	v_lshl_add_u64 v[176:177], s[90:91], 0, v[2:3]
	v_mov_b32_e32 v0, v1
	v_mov_b32_e32 v2, v1
	v_mov_b32_e32 v3, v1
	v_mov_b32_e32 v4, v1
	v_mov_b32_e32 v5, v1
	v_mov_b32_e32 v6, v1
	v_mov_b32_e32 v7, v1
	v_mov_b32_e32 v8, v1
	v_mov_b32_e32 v9, v1
	v_mov_b32_e32 v10, v1
	v_mov_b32_e32 v11, v1
	v_mov_b32_e32 v12, v1
	v_mov_b32_e32 v13, v1
	v_mov_b64_e32 v[128:129], v[14:15]
	v_mov_b64_e32 v[112:113], v[14:15]
	v_mov_b64_e32 v[96:97], v[14:15]
	v_mov_b64_e32 v[80:81], v[14:15]
	v_mov_b64_e32 v[64:65], v[14:15]
	v_mov_b64_e32 v[48:49], v[14:15]
	v_mov_b64_e32 v[32:33], v[14:15]
	v_mov_b64_e32 v[126:127], v[12:13]
	v_mov_b64_e32 v[124:125], v[10:11]
	v_mov_b64_e32 v[122:123], v[8:9]
	v_mov_b64_e32 v[120:121], v[6:7]
	v_mov_b64_e32 v[118:119], v[4:5]
	v_mov_b64_e32 v[116:117], v[2:3]
	v_mov_b64_e32 v[114:115], v[0:1]
	v_mov_b64_e32 v[110:111], v[12:13]
	v_mov_b64_e32 v[108:109], v[10:11]
	v_mov_b64_e32 v[106:107], v[8:9]
	v_mov_b64_e32 v[104:105], v[6:7]
	v_mov_b64_e32 v[102:103], v[4:5]
	v_mov_b64_e32 v[100:101], v[2:3]
	v_mov_b64_e32 v[98:99], v[0:1]
	v_mov_b64_e32 v[94:95], v[12:13]
	v_mov_b64_e32 v[92:93], v[10:11]
	v_mov_b64_e32 v[90:91], v[8:9]
	v_mov_b64_e32 v[88:89], v[6:7]
	v_mov_b64_e32 v[86:87], v[4:5]
	v_mov_b64_e32 v[84:85], v[2:3]
	v_mov_b64_e32 v[82:83], v[0:1]
	v_mov_b64_e32 v[78:79], v[12:13]
	v_mov_b64_e32 v[76:77], v[10:11]
	v_mov_b64_e32 v[74:75], v[8:9]
	v_mov_b64_e32 v[72:73], v[6:7]
	v_mov_b64_e32 v[70:71], v[4:5]
	v_mov_b64_e32 v[68:69], v[2:3]
	v_mov_b64_e32 v[66:67], v[0:1]
	v_mov_b64_e32 v[62:63], v[12:13]
	v_mov_b64_e32 v[60:61], v[10:11]
	v_mov_b64_e32 v[58:59], v[8:9]
	v_mov_b64_e32 v[56:57], v[6:7]
	v_mov_b64_e32 v[54:55], v[4:5]
	v_mov_b64_e32 v[52:53], v[2:3]
	v_mov_b64_e32 v[50:51], v[0:1]
	v_mov_b64_e32 v[46:47], v[12:13]
	v_mov_b64_e32 v[44:45], v[10:11]
	v_mov_b64_e32 v[42:43], v[8:9]
	v_mov_b64_e32 v[40:41], v[6:7]
	v_mov_b64_e32 v[38:39], v[4:5]
	v_mov_b64_e32 v[36:37], v[2:3]
	v_mov_b64_e32 v[34:35], v[0:1]
	v_mov_b64_e32 v[30:31], v[12:13]
	v_mov_b64_e32 v[28:29], v[10:11]
	v_mov_b64_e32 v[26:27], v[8:9]
	v_mov_b64_e32 v[24:25], v[6:7]
	v_mov_b64_e32 v[22:23], v[4:5]
	v_mov_b64_e32 v[20:21], v[2:3]
	v_mov_b64_e32 v[18:19], v[0:1]
	v_mov_b64_e32 v[16:17], v[14:15]
	s_mov_b32 s70, 1
	s_mov_b64 s[48:49], 0
	v_mov_b64_e32 v[14:15], v[12:13]
	v_mov_b64_e32 v[12:13], v[10:11]
	v_mov_b64_e32 v[10:11], v[8:9]
	v_mov_b64_e32 v[8:9], v[6:7]
	v_mov_b64_e32 v[6:7], v[4:5]
	v_mov_b64_e32 v[4:5], v[2:3]
	v_mov_b64_e32 v[2:3], v[0:1]
	s_branch .LBB0_501

; __device__ __forceinline__ int crow(int r, int hi) { return (r & 3) + 8 * (r >> 2) + 4 * hi; }
; template <class Epi>
; __device__ __forceinline__ void attn_rs_body(const bf16* __restrict__ Qb, const bf16* __restrict__ Kc, const bf16* __restrict__ V0c, const bf16* __restrict__ V1c, int NT, char* lds, const Epi& epi) {
;     ...
;     for (int j = 1; j <= NT; ++j) {
;       const int b = (j - 1) & 1;
;       const char* Pb = Pl + b * 16384;
;       const bf16x8 pa0 = *(const bf16x8*)(Pb), pa1 = *(const bf16x8*)(Pb + 1024), pa2 = *(const bf16x8*)(Pb + 2048), pa3 = *(const bf16x8*)(Pb + 3072);
;       const float flag = al[b * 256 + 32];
;       if (__builtin_amdgcn_readfirstlane(__float_as_uint(flag)) != 0u) {
;         float av[16];
; #pragma unroll
;         for (int r = 0; r < 16; ++r) av[r] = al[b * 256 + crow(r, hi)];
; #pragma unroll
;         for (int d = 0; d < 8; ++d)
; #pragma unroll
;           for (int r = 0; r < 16; ++r) o[d][r] *= av[r];
;       }
.LBB0_503:
	s_setprio 0
	v_mov_b32_e32 v0, s65
	ds_read_b32 v0, v0 offset:1152
	ds_read_b128 v[142:145], v179 offset:16384
	ds_read_b128 v[138:141], v179 offset:17408
	ds_read_b128 v[134:137], v179 offset:18432
	ds_read_b128 v[130:133], v179 offset:19456
	s_waitcnt lgkmcnt(0)
	v_readfirstlane_b32 s48, v0
	s_cmp_eq_u32 s48, 0
	s_cbranch_scc1 .LBB0_505
	v_add_u32_e32 v0, s65, v164
	ds_read_b128 v[158:161], v0 offset:1120
	ds_read_b128 v[154:157], v0 offset:1088
	ds_read_b128 v[150:153], v0 offset:1056
	ds_read_b128 v[146:149], v0 offset:1024
	s_waitcnt lgkmcnt(0)
	v_pk_mul_f32 v[126:127], v[126:127], v[158:159]
	v_pk_mul_f32 v[122:123], v[122:123], v[154:155]
	v_pk_mul_f32 v[118:119], v[118:119], v[150:151]
	v_pk_mul_f32 v[128:129], v[128:129], v[160:161]
	v_pk_mul_f32 v[124:125], v[124:125], v[156:157]
	v_pk_mul_f32 v[120:121], v[120:121], v[152:153]
	v_pk_mul_f32 v[116:117], v[116:117], v[148:149]
	v_pk_mul_f32 v[114:115], v[114:115], v[146:147]
	v_pk_mul_f32 v[110:111], v[110:111], v[158:159]
	v_pk_mul_f32 v[106:107], v[106:107], v[154:155]
	v_pk_mul_f32 v[102:103], v[102:103], v[150:151]
	v_pk_mul_f32 v[112:113], v[112:113], v[160:161]
	v_pk_mul_f32 v[108:109], v[108:109], v[156:157]
	v_pk_mul_f32 v[104:105], v[104:105], v[152:153]
	v_pk_mul_f32 v[100:101], v[100:101], v[148:149]
	v_pk_mul_f32 v[98:99], v[98:99], v[146:147]
	v_pk_mul_f32 v[94:95], v[94:95], v[158:159]
	v_pk_mul_f32 v[90:91], v[90:91], v[154:155]
	v_pk_mul_f32 v[86:87], v[86:87], v[150:151]
	v_pk_mul_f32 v[96:97], v[96:97], v[160:161]
	v_pk_mul_f32 v[92:93], v[92:93], v[156:157]
	v_pk_mul_f32 v[88:89], v[88:89], v[152:153]
	v_pk_mul_f32 v[84:85], v[84:85], v[148:149]
	v_pk_mul_f32 v[82:83], v[82:83], v[146:147]
	v_pk_mul_f32 v[78:79], v[78:79], v[158:159]
	v_pk_mul_f32 v[74:75], v[74:75], v[154:155]
	v_pk_mul_f32 v[70:71], v[70:71], v[150:151]
	v_pk_mul_f32 v[80:81], v[80:81], v[160:161]
	v_pk_mul_f32 v[76:77], v[76:77], v[156:157]
	v_pk_mul_f32 v[72:73], v[72:73], v[152:153]
	v_pk_mul_f32 v[68:69], v[68:69], v[148:149]
	v_pk_mul_f32 v[66:67], v[66:67], v[146:147]
	v_pk_mul_f32 v[62:63], v[62:63], v[158:159]
	v_pk_mul_f32 v[58:59], v[58:59], v[154:155]
	v_pk_mul_f32 v[54:55], v[54:55], v[150:151]
	v_pk_mul_f32 v[64:65], v[64:65], v[160:161]
	v_pk_mul_f32 v[60:61], v[60:61], v[156:157]
	v_pk_mul_f32 v[56:57], v[56:57], v[152:153]
	v_pk_mul_f32 v[52:53], v[52:53], v[148:149]
	v_pk_mul_f32 v[50:51], v[50:51], v[146:147]
	v_pk_mul_f32 v[46:47], v[46:47], v[158:159]
	v_pk_mul_f32 v[42:43], v[42:43], v[154:155]
	v_pk_mul_f32 v[38:39], v[38:39], v[150:151]
	v_pk_mul_f32 v[48:49], v[48:49], v[160:161]
	v_pk_mul_f32 v[44:45], v[44:45], v[156:157]
	v_pk_mul_f32 v[40:41], v[40:41], v[152:153]
	v_pk_mul_f32 v[36:37], v[36:37], v[148:149]
	v_pk_mul_f32 v[34:35], v[34:35], v[146:147]
	v_pk_mul_f32 v[30:31], v[30:31], v[158:159]
	v_pk_mul_f32 v[26:27], v[26:27], v[154:155]
	v_pk_mul_f32 v[22:23], v[22:23], v[150:151]
	v_pk_mul_f32 v[32:33], v[32:33], v[160:161]
	v_pk_mul_f32 v[28:29], v[28:29], v[156:157]
	v_pk_mul_f32 v[24:25], v[24:25], v[152:153]
	v_pk_mul_f32 v[20:21], v[20:21], v[148:149]
	v_pk_mul_f32 v[18:19], v[18:19], v[146:147]
	v_pk_mul_f32 v[14:15], v[14:15], v[158:159]
	v_pk_mul_f32 v[10:11], v[10:11], v[154:155]
	v_pk_mul_f32 v[6:7], v[6:7], v[150:151]
	v_pk_mul_f32 v[16:17], v[16:17], v[160:161]
	v_pk_mul_f32 v[12:13], v[12:13], v[156:157]
	v_pk_mul_f32 v[8:9], v[8:9], v[152:153]
	v_pk_mul_f32 v[4:5], v[4:5], v[148:149]
	v_pk_mul_f32 v[2:3], v[2:3], v[146:147]
